# speedup vs baseline: 1.0682x; 1.0185x over previous
.LBB0_470:
	s_or_b64 exec, exec, s[0:1]
	s_mov_b32 s0, 0x8000
	v_cmp_gt_i32_e32 vcc, s0, v2
	s_and_saveexec_b64 s[0:1], vcc
	s_cbranch_execz .LBB0_475
	v_mbcnt_lo_u32_b32 v1, -1, 0
	v_mbcnt_hi_u32_b32 v4, -1, v1
	v_and_b32_e32 v1, 64, v4
	v_add_u32_e32 v5, 64, v1
	v_xor_b32_e32 v1, 32, v4
	v_cmp_lt_i32_e32 vcc, v1, v5
	v_xor_b32_e32 v6, 16, v4
	v_and_b32_e32 v3, 63, v106
	v_cndmask_b32_e32 v1, v4, v1, vcc
	v_cmp_lt_i32_e32 vcc, v6, v5
	v_mov_b32_e32 v13, 0
	v_readlane_b32 s16, v254, 24
	v_cndmask_b32_e32 v6, v4, v6, vcc
	v_lshlrev_b32_e32 v16, 2, v6
	v_xor_b32_e32 v6, 8, v4
	v_cmp_lt_i32_e32 vcc, v6, v5
	v_lshlrev_b32_e32 v12, 2, v3
	v_readlane_b32 s2, v254, 0
	v_cndmask_b32_e32 v6, v4, v6, vcc
	v_lshlrev_b32_e32 v17, 2, v6
	v_xor_b32_e32 v6, 4, v4
	v_cmp_lt_i32_e32 vcc, v6, v5
	v_lshlrev_b32_e32 v8, 4, v3
	v_mov_b32_e32 v9, v13
	v_cndmask_b32_e32 v6, v4, v6, vcc
	s_waitcnt vmcnt(17)
	v_lshlrev_b32_e32 v18, 2, v6
	v_xor_b32_e32 v6, 2, v4
	v_cmp_lt_i32_e32 vcc, v6, v5
	v_readlane_b32 s17, v254, 25
	v_readlane_b32 s18, v254, 26
	v_cndmask_b32_e32 v6, v4, v6, vcc
	v_lshlrev_b32_e32 v19, 2, v6
	v_xor_b32_e32 v6, 1, v4
	v_cmp_lt_i32_e32 vcc, v6, v5
	v_readlane_b32 s19, v254, 27
	v_readlane_b32 s20, v254, 28
	v_cndmask_b32_e32 v4, v4, v6, vcc
	v_readlane_b32 s21, v254, 29
	v_lshlrev_b32_e32 v10, 3, v3
	v_mov_b32_e32 v11, v13
	v_cmp_eq_u32_e64 s[4:5], 0, v3
	s_lshl_b32 s12, s2, 2
	v_lshlrev_b32_e32 v1, 2, v1
	v_lshlrev_b32_e32 v20, 2, v4
	v_lshl_add_u64 v[4:5], s[16:17], 0, v[8:9]
	v_lshl_add_u64 v[6:7], s[18:19], 0, v[8:9]
	v_lshl_add_u64 v[8:9], s[82:83], 0, v[8:9]
	v_lshl_add_u64 v[10:11], s[20:21], 0, v[10:11]
	v_lshl_add_u64 v[12:13], s[94:95], 0, v[12:13]
	s_mov_b64 s[10:11], 0
	v_mov_b32_e32 v21, 0x3727c5ac
	s_mov_b32 s13, 0x800000
	s_mov_b32 s14, 0x42fe0000
	s_mov_b32 s15, 0x40c0c00
	s_movk_i32 s16, 0x7fff
	v_readlane_b32 s3, v254, 1
	v_readlane_b32 s22, v254, 30
	v_readlane_b32 s23, v254, 31
	v_readlane_b32 s24, v254, 32
	v_readlane_b32 s25, v254, 33
	v_readlane_b32 s26, v254, 34
	v_readlane_b32 s27, v254, 35
	v_readlane_b32 s28, v254, 36
	v_readlane_b32 s29, v254, 37
	v_readlane_b32 s30, v254, 38
	v_readlane_b32 s31, v254, 39
	global_load_dwordx4 v[200:203], v[4:5], off
	global_load_dwordx4 v[204:207], v[6:7], off
	global_load_dwordx4 v[208:211], v[4:5], off offset:1024
	global_load_dwordx4 v[212:215], v[6:7], off offset:1024
	global_load_dwordx4 v[216:219], v[4:5], off offset:2048
	global_load_dwordx4 v[220:223], v[6:7], off offset:2048
	global_load_dwordx4 v[224:227], v[4:5], off offset:3072
	global_load_dwordx4 v[228:231], v[6:7], off offset:3072
	s_waitcnt vmcnt(0)
	s_branch .LBB0_473

.LBB0_473:
	v_ashrrev_i32_e32 v3, 31, v2
	v_lshlrev_b64 v[14:15], 12, v[2:3]
	v_lshl_add_u64 v[14:15], v[8:9], 0, v[14:15]
	s_waitcnt lgkmcnt(0)
	global_load_dwordx4 v[22:25], v[14:15], off
	global_load_dwordx4 v[26:29], v[14:15], off offset:1024
	global_load_dwordx4 v[30:33], v[14:15], off offset:2048
	global_load_dwordx4 v[34:37], v[14:15], off offset:3072
	s_waitcnt vmcnt(3)
	v_mov_b32_e32 v38, v22
	s_waitcnt vmcnt(2)
	v_mov_b32_e32 v39, v26
	v_mov_b32_e32 v40, v23
	v_mov_b32_e32 v41, v27
	v_mov_b32_e32 v42, v24
	v_mov_b32_e32 v43, v28
	v_pk_add_f32 v[38:39], v[38:39], v[40:41]
	v_mov_b32_e32 v44, v25
	v_mov_b32_e32 v45, v29
	s_waitcnt vmcnt(1)
	v_mov_b32_e32 v46, v30
	s_waitcnt vmcnt(0)
	v_mov_b32_e32 v47, v34
	v_mov_b32_e32 v48, v31
	v_mov_b32_e32 v49, v35
	v_pk_add_f32 v[38:39], v[38:39], v[42:43]
	v_mov_b32_e32 v50, v32
	v_mov_b32_e32 v51, v36
	v_pk_add_f32 v[40:41], v[46:47], v[48:49]
	v_pk_add_f32 v[38:39], v[38:39], v[44:45]
	v_mov_b32_e32 v52, v33
	v_mov_b32_e32 v53, v37
	v_pk_add_f32 v[40:41], v[40:41], v[50:51]
	v_add_f32_e32 v38, 0, v38
	v_pk_add_f32 v[40:41], v[40:41], v[52:53]
	v_add_f32_e32 v38, v38, v39
	v_add_f32_e32 v38, v38, v40
	v_add_f32_e32 v38, v38, v41
	ds_bpermute_b32 v39, v1, v38
	s_waitcnt lgkmcnt(0)
	v_add_f32_e32 v38, v38, v39
	ds_bpermute_b32 v39, v16, v38
	s_waitcnt lgkmcnt(0)
	v_add_f32_e32 v38, v38, v39
	ds_bpermute_b32 v39, v17, v38
	s_waitcnt lgkmcnt(0)
	v_add_f32_e32 v38, v38, v39
	ds_bpermute_b32 v39, v18, v38
	s_waitcnt lgkmcnt(0)
	v_add_f32_e32 v38, v38, v39
	ds_bpermute_b32 v39, v19, v38
	s_waitcnt lgkmcnt(0)
	v_add_f32_e32 v46, v38, v39
	v_mov_b64_e32 v[38:39], v[200:201]
	v_mov_b64_e32 v[40:41], v[202:203]
	v_mov_b64_e32 v[42:43], v[204:205]
	v_mov_b64_e32 v[44:45], v[206:207]
	ds_bpermute_b32 v47, v20, v46
	s_waitcnt lgkmcnt(0)
	v_add_f32_e32 v46, v46, v47
	v_mul_f32_e32 v46, 0x3a800000, v46
	v_pk_add_f32 v[22:23], v[22:23], v[46:47] op_sel_hi:[1,0] neg_lo:[0,1] neg_hi:[0,1]
	v_pk_add_f32 v[48:49], v[26:27], v[46:47] op_sel_hi:[1,0] neg_lo:[0,1] neg_hi:[0,1]
	v_pk_add_f32 v[50:51], v[28:29], v[46:47] op_sel_hi:[1,0] neg_lo:[0,1] neg_hi:[0,1]
	v_pk_add_f32 v[52:53], v[30:31], v[46:47] op_sel_hi:[1,0] neg_lo:[0,1] neg_hi:[0,1]
	v_pk_add_f32 v[56:57], v[34:35], v[46:47] op_sel_hi:[1,0] neg_lo:[0,1] neg_hi:[0,1]
	v_mov_b32_e32 v28, v23
	v_mov_b32_e32 v29, v49
	v_pk_add_f32 v[24:25], v[24:25], v[46:47] op_sel_hi:[1,0] neg_lo:[0,1] neg_hi:[0,1]
	v_pk_add_f32 v[54:55], v[32:33], v[46:47] op_sel_hi:[1,0] neg_lo:[0,1] neg_hi:[0,1]
	v_pk_add_f32 v[46:47], v[36:37], v[46:47] op_sel_hi:[1,0] neg_lo:[0,1] neg_hi:[0,1]
	v_mov_b32_e32 v26, v22
	v_mov_b32_e32 v27, v48
	v_mov_b32_e32 v36, v57
	v_mov_b32_e32 v37, v53
	v_pk_mul_f32 v[28:29], v[28:29], v[28:29]
	v_mov_b32_e32 v30, v24
	v_mov_b32_e32 v31, v50
	v_mov_b32_e32 v34, v56
	v_mov_b32_e32 v35, v52
	v_pk_mul_f32 v[36:37], v[36:37], v[36:37]
	v_pk_fma_f32 v[26:27], v[26:27], v[26:27], v[28:29]
	v_mov_b32_e32 v32, v25
	v_mov_b32_e32 v33, v51
	v_mov_b32_e32 v58, v46
	v_mov_b32_e32 v59, v54
	v_pk_fma_f32 v[28:29], v[34:35], v[34:35], v[36:37]
	v_pk_fma_f32 v[26:27], v[30:31], v[30:31], v[26:27]
	v_mov_b32_e32 v60, v47
	v_mov_b32_e32 v61, v55
	v_pk_fma_f32 v[28:29], v[58:59], v[58:59], v[28:29]
	v_pk_fma_f32 v[26:27], v[32:33], v[32:33], v[26:27]
	v_pk_fma_f32 v[28:29], v[60:61], v[60:61], v[28:29]
	v_add_f32_e32 v26, v26, v27
	v_add_f32_e32 v26, v29, v26
	v_add_f32_e32 v26, v28, v26
	ds_bpermute_b32 v27, v1, v26
	s_waitcnt lgkmcnt(0)
	v_add_f32_e32 v26, v26, v27
	ds_bpermute_b32 v27, v16, v26
	s_waitcnt lgkmcnt(0)
	v_add_f32_e32 v26, v26, v27
	ds_bpermute_b32 v27, v17, v26
	s_waitcnt lgkmcnt(0)
	v_add_f32_e32 v26, v26, v27
	ds_bpermute_b32 v27, v18, v26
	s_waitcnt lgkmcnt(0)
	v_add_f32_e32 v26, v26, v27
	ds_bpermute_b32 v27, v19, v26
	s_waitcnt lgkmcnt(0)
	v_add_f32_e32 v26, v26, v27
	ds_bpermute_b32 v27, v20, v26
	s_waitcnt lgkmcnt(0)
	v_add_f32_e32 v26, v26, v27
	v_fmamk_f32 v26, v26, 0x3a800000, v21
	v_mul_f32_e32 v27, 0x4b800000, v26
	v_cmp_gt_f32_e32 vcc, s13, v26
	s_nop 1
	v_cndmask_b32_e32 v26, v26, v27, vcc
	v_rsq_f32_e32 v28, v26
	v_lshlrev_b64 v[26:27], 11, v[2:3]
	v_lshl_add_u64 v[58:59], v[10:11], 0, v[26:27]
	v_mul_f32_e32 v26, 0x45800000, v28
	v_cndmask_b32_e32 v60, v28, v26, vcc
	v_pk_mul_f32 v[22:23], v[22:23], v[60:61] op_sel_hi:[1,0]
	v_pk_mul_f32 v[24:25], v[24:25], v[60:61] op_sel_hi:[1,0]
	v_pk_fma_f32 v[22:23], v[38:39], v[22:23], v[42:43]
	v_pk_fma_f32 v[24:25], v[40:41], v[24:25], v[44:45]
	v_cvt_pk_bf16_f32 v26, v22, v23
	v_cvt_pk_bf16_f32 v27, v24, v25
	global_store_dwordx4 v[14:15], v[22:25], off
	v_mov_b64_e32 v[26:27], v[208:209]
	v_mov_b64_e32 v[28:29], v[210:211]
	s_nop 0
	v_mov_b64_e32 v[30:31], v[212:213]
	v_mov_b64_e32 v[32:33], v[214:215]
	v_pk_mul_f32 v[34:35], v[48:49], v[60:61] op_sel_hi:[1,0]
	v_pk_mul_f32 v[36:37], v[50:51], v[60:61] op_sel_hi:[1,0]
	v_pk_mul_f32 v[38:39], v[52:53], v[60:61] op_sel_hi:[1,0]
	v_pk_mul_f32 v[40:41], v[54:55], v[60:61] op_sel_hi:[1,0]
	v_pk_mul_f32 v[44:45], v[46:47], v[60:61] op_sel_hi:[1,0]
	v_max_f32_e64 v46, |v24|, |v25|
	v_pk_mul_f32 v[42:43], v[56:57], v[60:61] op_sel_hi:[1,0]
	v_max3_f32 v46, |v22|, |v23|, v46
	v_pk_fma_f32 v[26:27], v[26:27], v[34:35], v[30:31]
	v_pk_fma_f32 v[28:29], v[28:29], v[36:37], v[32:33]
	v_cvt_pk_bf16_f32 v30, v26, v27
	v_cvt_pk_bf16_f32 v31, v28, v29
	global_store_dwordx4 v[14:15], v[26:29], off offset:1024
	v_mov_b64_e32 v[30:31], v[216:217]
	v_mov_b64_e32 v[32:33], v[218:219]
	s_nop 0
	v_mov_b64_e32 v[34:35], v[220:221]
	v_mov_b64_e32 v[36:37], v[222:223]
	v_max_f32_e64 v47, |v28|, |v29|
	v_max3_f32 v47, |v26|, |v27|, v47
	v_max3_f32 v46, v46, 0, v47
	v_pk_fma_f32 v[30:31], v[38:39], v[30:31], v[34:35]
	v_pk_fma_f32 v[32:33], v[40:41], v[32:33], v[36:37]
	v_cvt_pk_bf16_f32 v34, v30, v31
	v_cvt_pk_bf16_f32 v35, v32, v33
	global_store_dwordx4 v[14:15], v[30:33], off offset:2048
	v_mov_b64_e32 v[34:35], v[224:225]
	v_mov_b64_e32 v[36:37], v[226:227]
	s_nop 0
	v_mov_b64_e32 v[38:39], v[228:229]
	v_mov_b64_e32 v[40:41], v[230:231]
	v_max_f32_e64 v47, |v32|, |v33|
	v_max3_f32 v47, |v30|, |v31|, v47
	v_pk_fma_f32 v[36:37], v[44:45], v[36:37], v[40:41]
	v_pk_fma_f32 v[34:35], v[42:43], v[34:35], v[38:39]
	v_max_f32_e64 v38, |v36|, |v37|
	v_max3_f32 v38, |v34|, |v35|, v38
	v_max3_f32 v38, v46, v47, v38
	ds_bpermute_b32 v39, v1, v38
	global_store_dwordx4 v[14:15], v[34:37], off offset:3072
	s_waitcnt lgkmcnt(0)
	v_max_f32_e32 v39, v39, v39
	v_max_f32_e32 v38, v38, v39
	ds_bpermute_b32 v39, v16, v38
	s_waitcnt lgkmcnt(0)
	v_max_f32_e32 v39, v39, v39
	v_max_f32_e32 v38, v38, v39
	ds_bpermute_b32 v39, v17, v38
	s_waitcnt lgkmcnt(0)
	v_max_f32_e32 v39, v39, v39
	v_max_f32_e32 v38, v38, v39
	ds_bpermute_b32 v39, v18, v38
	s_waitcnt lgkmcnt(0)
	v_max_f32_e32 v39, v39, v39
	v_max_f32_e32 v40, v38, v39
	ds_bpermute_b32 v41, v19, v40
	v_lshlrev_b64 v[38:39], 10, v[2:3]
	v_lshl_add_u64 v[38:39], v[12:13], 0, v[38:39]
	s_waitcnt lgkmcnt(0)
	v_max_f32_e32 v41, v41, v41
	v_max_f32_e32 v42, v40, v41
	ds_bpermute_b32 v43, v20, v42
	v_cvt_pk_bf16_f32 v40, v34, v35
	v_cvt_pk_bf16_f32 v41, v36, v37
	s_waitcnt lgkmcnt(0)
	v_max_f32_e32 v14, v43, v43
	v_max_f32_e32 v14, v42, v14
	v_div_scale_f32 v15, s[2:3], v14, v14, s14
	v_rcp_f32_e32 v42, v15
	v_div_scale_f32 v40, vcc, s14, v14, s14
	v_cmp_lt_f32_e64 s[6:7], 0, v14
	v_fma_f32 v41, -v15, v42, 1.0
	v_fmac_f32_e32 v42, v41, v42
	v_mul_f32_e32 v41, v40, v42
	v_fma_f32 v43, -v15, v41, v40
	v_fmac_f32_e32 v41, v43, v42
	v_fma_f32 v15, -v15, v41, v40
	v_div_fmas_f32 v15, v15, v42, v41
	v_div_fixup_f32 v15, v15, v14, s14
	v_cndmask_b32_e64 v15, 0, v15, s[6:7]
	v_mul_f32_e32 v22, v22, v15
	v_mul_f32_e32 v23, v23, v15
	v_mul_f32_e32 v24, v24, v15
	v_mul_f32_e32 v25, v25, v15
	v_mul_f32_e32 v26, v26, v15
	v_mul_f32_e32 v27, v27, v15
	v_mul_f32_e32 v28, v28, v15
	v_mul_f32_e32 v29, v29, v15
	v_rndne_f32_e32 v22, v22
	v_rndne_f32_e32 v23, v23
	v_rndne_f32_e32 v24, v24
	v_rndne_f32_e32 v25, v25
	v_rndne_f32_e32 v26, v26
	v_rndne_f32_e32 v27, v27
	v_mul_f32_e32 v30, v30, v15
	v_mul_f32_e32 v31, v31, v15
	v_mul_f32_e32 v32, v32, v15
	v_mul_f32_e32 v33, v33, v15
	v_mul_f32_e32 v34, v34, v15
	v_mul_f32_e32 v35, v35, v15
	v_mul_f32_e32 v36, v36, v15
	v_mul_f32_e32 v15, v37, v15
	v_rndne_f32_e32 v28, v28
	v_rndne_f32_e32 v29, v29
	v_add_f32_e32 v37, v22, v23
	v_add_f32_e32 v40, v24, v25
	v_cvt_i32_f32_e32 v22, v22
	v_cvt_i32_f32_e32 v23, v23
	v_cvt_i32_f32_e32 v25, v25
	v_add_f32_e32 v41, v26, v27
	v_cvt_i32_f32_e32 v27, v27
	v_rndne_f32_e32 v30, v30
	v_rndne_f32_e32 v31, v31
	v_rndne_f32_e32 v32, v32
	v_rndne_f32_e32 v33, v33
	v_cvt_i32_f32_sdwa v24, v24 dst_sel:WORD_1 dst_unused:UNUSED_PAD src0_sel:DWORD
	v_add_f32_e32 v42, v28, v29
	v_add_f32_e32 v37, v37, v40
	v_rndne_f32_e32 v34, v34
	v_rndne_f32_e32 v35, v35
	v_rndne_f32_e32 v36, v36
	v_rndne_f32_e32 v15, v15
	v_add_f32_e32 v43, v30, v31
	v_add_f32_e32 v44, v32, v33
	v_add_f32_e32 v40, v41, v42
	v_add_f32_e32 v37, 0, v37
	v_add_f32_e32 v45, v34, v35
	v_add_f32_e32 v46, v36, v15
	v_add_f32_e32 v41, v43, v44
	v_add_f32_e32 v37, v40, v37
	v_add_f32_e32 v42, v45, v46
	v_lshlrev_b32_e32 v23, 8, v23
	v_perm_b32 v22, v25, v22, s15
	v_lshlrev_b32_e32 v25, 8, v27
	v_add_f32_e32 v27, v41, v37
	v_cvt_i32_f32_e32 v26, v26
	v_cvt_i32_f32_sdwa v28, v28 dst_sel:WORD_1 dst_unused:UNUSED_PAD src0_sel:DWORD
	v_cvt_i32_f32_e32 v29, v29
	v_and_b32_e32 v24, 0xff0000, v24
	v_and_b32_e32 v23, 0xff00, v23
	v_add_f32_e32 v27, v42, v27
	v_or3_b32 v22, v22, v23, v24
	ds_bpermute_b32 v23, v1, v27
	v_and_b32_e32 v25, 0xff00, v25
	global_store_dword v[38:39], v22, off
	v_and_b32_e32 v22, 0xff0000, v28
	v_perm_b32 v24, v29, v26, s15
	v_or3_b32 v22, v24, v25, v22
	global_store_dword v[38:39], v22, off offset:256
	s_waitcnt lgkmcnt(0)
	v_add_f32_e32 v22, v27, v23
	ds_bpermute_b32 v23, v16, v22
	v_cvt_i32_f32_e32 v25, v31
	v_cvt_i32_f32_e32 v24, v30
	v_cvt_i32_f32_sdwa v26, v32 dst_sel:WORD_1 dst_unused:UNUSED_PAD src0_sel:DWORD
	v_cvt_i32_f32_e32 v27, v33
	s_waitcnt lgkmcnt(0)
	v_add_f32_e32 v22, v22, v23
	ds_bpermute_b32 v23, v17, v22
	v_lshlrev_b32_e32 v25, 8, v25
	v_and_b32_e32 v25, 0xff00, v25
	v_and_b32_e32 v26, 0xff0000, v26
	v_perm_b32 v24, v27, v24, s15
	s_waitcnt lgkmcnt(0)
	v_add_f32_e32 v22, v22, v23
	ds_bpermute_b32 v23, v18, v22
	v_or3_b32 v24, v24, v25, v26
	v_cvt_i32_f32_e32 v25, v35
	v_cvt_i32_f32_e32 v27, v15
	global_store_dword v[38:39], v24, off offset:512
	s_waitcnt lgkmcnt(0)
	v_add_f32_e32 v22, v22, v23
	ds_bpermute_b32 v23, v19, v22
	v_lshlrev_b32_e32 v15, 8, v25
	v_cvt_i32_f32_e32 v24, v34
	v_cvt_i32_f32_sdwa v26, v36 dst_sel:WORD_1 dst_unused:UNUSED_PAD src0_sel:DWORD
	v_and_b32_e32 v25, 0xff00, v15
	s_waitcnt lgkmcnt(0)
	v_add_f32_e32 v15, v22, v23
	ds_bpermute_b32 v22, v20, v15
	v_and_b32_e32 v23, 0xff0000, v26
	v_perm_b32 v24, v27, v24, s15
	v_or3_b32 v23, v24, v25, v23
	global_store_dword v[38:39], v23, off offset:768
	s_and_saveexec_b64 s[2:3], s[4:5]
	s_cbranch_execz .LBB0_472
	v_div_scale_f32 v23, s[18:19], s14, s14, v14
	v_rcp_f32_e32 v24, v23
	s_waitcnt lgkmcnt(0)
	v_add_f32_e32 v25, v15, v22
	v_fma_f32 v15, -v23, v24, 1.0
	v_fmac_f32_e32 v24, v15, v24
	v_div_scale_f32 v15, vcc, v14, s14, v14
	v_mul_f32_e32 v22, v15, v24
	v_fma_f32 v26, -v23, v22, v15
	v_fmac_f32_e32 v22, v26, v24
	v_fma_f32 v15, -v23, v22, v15
	v_div_fmas_f32 v15, v15, v24, v22
	v_div_fixup_f32 v14, v15, s14, v14
	v_cndmask_b32_e64 v24, 0, v14, s[6:7]
	v_lshlrev_b64 v[14:15], 2, v[2:3]
	v_lshl_add_u64 v[22:23], s[68:69], 0, v[14:15]
	v_lshl_add_u64 v[14:15], s[70:71], 0, v[14:15]
	global_store_dword v[22:23], v24, off
	global_store_dword v[14:15], v25, off
	s_branch .LBB0_472

.LBB0_841:
	v_lshrrev_b32_e32 v0, 6, v106
	v_lshl_add_u32 v0, s96, 2, v0
	s_mov_b32 s0, 0x8000
	v_cmp_gt_i32_e32 vcc, s0, v0
	s_and_saveexec_b64 s[0:1], vcc
	s_cbranch_execz .LBB0_846
	v_mbcnt_lo_u32_b32 v2, -1, 0
	v_mbcnt_hi_u32_b32 v2, -1, v2
	v_and_b32_e32 v3, 64, v2
	v_add_u32_e32 v3, 64, v3
	v_xor_b32_e32 v4, 32, v2
	v_cmp_lt_i32_e32 vcc, v4, v3
	v_readlane_b32 s12, v254, 24
	v_readlane_b32 s14, v254, 26
	v_cndmask_b32_e32 v4, v2, v4, vcc
	s_waitcnt vmcnt(18)
	v_lshlrev_b32_e32 v26, 2, v4
	v_xor_b32_e32 v4, 16, v2
	v_cmp_lt_i32_e32 vcc, v4, v3
	v_readlane_b32 s15, v254, 27
	s_add_u32 s2, s14, 0x2000
	v_cndmask_b32_e32 v4, v2, v4, vcc
	v_lshlrev_b32_e32 v27, 2, v4
	v_xor_b32_e32 v4, 8, v2
	v_cmp_lt_i32_e32 vcc, v4, v3
	s_addc_u32 s3, s15, 0
	v_and_b32_e32 v1, 63, v106
	v_cndmask_b32_e32 v4, v2, v4, vcc
	v_lshlrev_b32_e32 v28, 2, v4
	v_xor_b32_e32 v4, 4, v2
	v_cmp_lt_i32_e32 vcc, v4, v3
	v_readlane_b32 s13, v254, 25
	s_add_u32 s6, s12, 0x2000
	v_cndmask_b32_e32 v4, v2, v4, vcc
	v_lshlrev_b32_e32 v29, 2, v4
	v_xor_b32_e32 v4, 2, v2
	v_cmp_lt_i32_e32 vcc, v4, v3
	v_readlane_b32 s10, v254, 0
	v_mov_b32_e32 v23, 0
	v_cndmask_b32_e32 v4, v2, v4, vcc
	s_waitcnt vmcnt(16)
	v_lshlrev_b32_e32 v30, 2, v4
	v_xor_b32_e32 v4, 1, v2
	v_lshlrev_b32_e32 v18, 4, v1
	v_cmp_lt_i32_e32 vcc, v4, v3
	v_readlane_b32 s16, v254, 28
	v_readlane_b32 s17, v254, 29
	s_addc_u32 s7, s13, 0
	s_waitcnt lgkmcnt(0)
	v_lshlrev_b32_e32 v22, 2, v1
	v_readlane_b32 s11, v254, 1
	v_cndmask_b32_e32 v2, v2, v4, vcc
	v_mov_b32_e32 v19, v23
	v_or_b32_e32 v8, 0x400, v18
	v_mov_b32_e32 v9, v23
	v_or_b32_e32 v12, 0x800, v18
	v_mov_b32_e32 v13, v23
	v_or_b32_e32 v16, 0xc00, v18
	v_mov_b32_e32 v17, v23
	v_lshlrev_b32_e32 v20, 3, v1
	v_mov_b32_e32 v21, v23
	v_cmp_eq_u32_e64 s[4:5], 0, v1
	s_lshl_b32 s12, s10, 2
	v_lshlrev_b32_e32 v31, 2, v2
	v_lshl_add_u64 v[2:3], s[6:7], 0, v[18:19]
	v_lshl_add_u64 v[4:5], s[2:3], 0, v[18:19]
	v_lshl_add_u64 v[6:7], s[6:7], 0, v[8:9]
	v_lshl_add_u64 v[8:9], s[2:3], 0, v[8:9]
	v_lshl_add_u64 v[10:11], s[6:7], 0, v[12:13]
	v_lshl_add_u64 v[12:13], s[2:3], 0, v[12:13]
	v_lshl_add_u64 v[14:15], s[6:7], 0, v[16:17]
	v_lshl_add_u64 v[16:17], s[2:3], 0, v[16:17]
	v_lshl_add_u64 v[18:19], s[82:83], 0, v[18:19]
	v_lshl_add_u64 v[20:21], s[16:17], 0, v[20:21]
	v_lshl_add_u64 v[22:23], s[94:95], 0, v[22:23]
	s_mov_b64 s[10:11], 0
	v_mov_b32_e32 v32, 0x3727c5ac
	s_mov_b32 s13, 0x800000
	s_mov_b32 s14, 0x42fe0000
	s_mov_b32 s15, 0x40c0c00
	s_movk_i32 s16, 0x7fff
	v_readlane_b32 s18, v254, 30
	v_readlane_b32 s19, v254, 31
	v_readlane_b32 s20, v254, 32
	v_readlane_b32 s21, v254, 33
	v_readlane_b32 s22, v254, 34
	v_readlane_b32 s23, v254, 35
	v_readlane_b32 s24, v254, 36
	v_readlane_b32 s25, v254, 37
	v_readlane_b32 s26, v254, 38
	v_readlane_b32 s27, v254, 39
	global_load_dwordx4 v[200:203], v[2:3], off
	global_load_dwordx4 v[204:207], v[4:5], off
	global_load_dwordx4 v[208:211], v[6:7], off
	global_load_dwordx4 v[212:215], v[8:9], off
	global_load_dwordx4 v[216:219], v[10:11], off
	global_load_dwordx4 v[220:223], v[12:13], off
	global_load_dwordx4 v[224:227], v[14:15], off
	global_load_dwordx4 v[228:231], v[16:17], off
	s_waitcnt vmcnt(0)
	s_branch .LBB0_844

.LBB0_844:
	v_ashrrev_i32_e32 v1, 31, v0
	v_lshlrev_b64 v[24:25], 12, v[0:1]
	v_lshl_add_u64 v[24:25], v[18:19], 0, v[24:25]
	global_load_dwordx4 v[34:37], v[24:25], off
	global_load_dwordx4 v[38:41], v[24:25], off offset:1024
	global_load_dwordx4 v[42:45], v[24:25], off offset:2048
	global_load_dwordx4 v[46:49], v[24:25], off offset:3072
	s_waitcnt vmcnt(3)
	v_mov_b32_e32 v50, v34
	s_waitcnt vmcnt(2)
	v_mov_b32_e32 v51, v38
	v_mov_b32_e32 v52, v35
	v_mov_b32_e32 v53, v39
	v_mov_b32_e32 v54, v36
	v_mov_b32_e32 v55, v40
	v_pk_add_f32 v[50:51], v[50:51], v[52:53]
	v_mov_b32_e32 v56, v37
	v_mov_b32_e32 v57, v41
	s_waitcnt vmcnt(1)
	v_mov_b32_e32 v58, v42
	s_waitcnt vmcnt(0)
	v_mov_b32_e32 v59, v46
	v_mov_b32_e32 v60, v43
	v_mov_b32_e32 v61, v47
	v_pk_add_f32 v[50:51], v[50:51], v[54:55]
	v_mov_b32_e32 v62, v44
	v_mov_b32_e32 v63, v48
	v_pk_add_f32 v[52:53], v[58:59], v[60:61]
	v_pk_add_f32 v[50:51], v[50:51], v[56:57]
	v_mov_b32_e32 v64, v45
	v_mov_b32_e32 v65, v49
	v_pk_add_f32 v[52:53], v[52:53], v[62:63]
	s_waitcnt lgkmcnt(0)
	v_add_f32_e32 v33, 0, v50
	v_pk_add_f32 v[52:53], v[52:53], v[64:65]
	v_add_f32_e32 v33, v33, v51
	v_add_f32_e32 v33, v33, v52
	v_add_f32_e32 v33, v33, v53
	ds_bpermute_b32 v50, v26, v33
	s_waitcnt lgkmcnt(0)
	v_add_f32_e32 v33, v33, v50
	ds_bpermute_b32 v50, v27, v33
	s_waitcnt lgkmcnt(0)
	v_add_f32_e32 v33, v33, v50
	ds_bpermute_b32 v50, v28, v33
	s_waitcnt lgkmcnt(0)
	v_add_f32_e32 v33, v33, v50
	ds_bpermute_b32 v50, v29, v33
	s_waitcnt lgkmcnt(0)
	v_add_f32_e32 v33, v33, v50
	ds_bpermute_b32 v50, v30, v33
	s_waitcnt lgkmcnt(0)
	v_add_f32_e32 v33, v33, v50
	v_mov_b64_e32 v[50:51], v[200:201]
	v_mov_b64_e32 v[52:53], v[202:203]
	v_mov_b64_e32 v[54:55], v[204:205]
	v_mov_b64_e32 v[56:57], v[206:207]
	ds_bpermute_b32 v58, v31, v33
	s_waitcnt lgkmcnt(0)
	v_add_f32_e32 v33, v33, v58
	v_mul_f32_e32 v58, 0x3a800000, v33
	v_pk_add_f32 v[34:35], v[34:35], v[58:59] op_sel_hi:[1,0] neg_lo:[0,1] neg_hi:[0,1]
	v_pk_add_f32 v[60:61], v[38:39], v[58:59] op_sel_hi:[1,0] neg_lo:[0,1] neg_hi:[0,1]
	v_pk_add_f32 v[62:63], v[40:41], v[58:59] op_sel_hi:[1,0] neg_lo:[0,1] neg_hi:[0,1]
	v_pk_add_f32 v[64:65], v[42:43], v[58:59] op_sel_hi:[1,0] neg_lo:[0,1] neg_hi:[0,1]
	v_pk_add_f32 v[68:69], v[46:47], v[58:59] op_sel_hi:[1,0] neg_lo:[0,1] neg_hi:[0,1]
	v_mov_b32_e32 v40, v35
	v_mov_b32_e32 v41, v61
	v_pk_add_f32 v[36:37], v[36:37], v[58:59] op_sel_hi:[1,0] neg_lo:[0,1] neg_hi:[0,1]
	v_pk_add_f32 v[66:67], v[44:45], v[58:59] op_sel_hi:[1,0] neg_lo:[0,1] neg_hi:[0,1]
	v_pk_add_f32 v[58:59], v[48:49], v[58:59] op_sel_hi:[1,0] neg_lo:[0,1] neg_hi:[0,1]
	v_mov_b32_e32 v38, v34
	v_mov_b32_e32 v39, v60
	v_mov_b32_e32 v48, v69
	v_mov_b32_e32 v49, v65
	v_pk_mul_f32 v[40:41], v[40:41], v[40:41]
	v_mov_b32_e32 v42, v36
	v_mov_b32_e32 v43, v62
	v_mov_b32_e32 v46, v68
	v_mov_b32_e32 v47, v64
	v_pk_mul_f32 v[48:49], v[48:49], v[48:49]
	v_pk_fma_f32 v[38:39], v[38:39], v[38:39], v[40:41]
	v_mov_b32_e32 v44, v37
	v_mov_b32_e32 v45, v63
	v_mov_b32_e32 v70, v58
	v_mov_b32_e32 v71, v66
	v_pk_fma_f32 v[40:41], v[46:47], v[46:47], v[48:49]
	v_pk_fma_f32 v[38:39], v[42:43], v[42:43], v[38:39]
	v_mov_b32_e32 v72, v59
	v_mov_b32_e32 v73, v67
	v_pk_fma_f32 v[40:41], v[70:71], v[70:71], v[40:41]
	v_pk_fma_f32 v[38:39], v[44:45], v[44:45], v[38:39]
	v_pk_fma_f32 v[40:41], v[72:73], v[72:73], v[40:41]
	v_add_f32_e32 v33, v38, v39
	v_add_f32_e32 v33, v41, v33
	v_add_f32_e32 v33, v40, v33
	ds_bpermute_b32 v38, v26, v33
	s_waitcnt lgkmcnt(0)
	v_add_f32_e32 v33, v33, v38
	ds_bpermute_b32 v38, v27, v33
	s_waitcnt lgkmcnt(0)
	v_add_f32_e32 v33, v33, v38
	ds_bpermute_b32 v38, v28, v33
	s_waitcnt lgkmcnt(0)
	v_add_f32_e32 v33, v33, v38
	ds_bpermute_b32 v38, v29, v33
	s_waitcnt lgkmcnt(0)
	v_add_f32_e32 v33, v33, v38
	ds_bpermute_b32 v38, v30, v33
	s_waitcnt lgkmcnt(0)
	v_add_f32_e32 v33, v33, v38
	ds_bpermute_b32 v38, v31, v33
	s_waitcnt lgkmcnt(0)
	v_add_f32_e32 v33, v33, v38
	v_fmamk_f32 v33, v33, 0x3a800000, v32
	v_mul_f32_e32 v38, 0x4b800000, v33
	v_cmp_gt_f32_e32 vcc, s13, v33
	s_nop 1
	v_cndmask_b32_e32 v33, v33, v38, vcc
	v_rsq_f32_e32 v33, v33
	v_lshlrev_b64 v[38:39], 11, v[0:1]
	v_lshl_add_u64 v[70:71], v[20:21], 0, v[38:39]
	v_mul_f32_e32 v38, 0x45800000, v33
	v_cndmask_b32_e32 v72, v33, v38, vcc
	v_pk_mul_f32 v[34:35], v[34:35], v[72:73] op_sel_hi:[1,0]
	v_pk_mul_f32 v[36:37], v[36:37], v[72:73] op_sel_hi:[1,0]
	v_pk_fma_f32 v[34:35], v[50:51], v[34:35], v[54:55]
	v_pk_fma_f32 v[36:37], v[52:53], v[36:37], v[56:57]
	v_cvt_pk_bf16_f32 v38, v34, v35
	v_cvt_pk_bf16_f32 v39, v36, v37
	global_store_dwordx4 v[24:25], v[34:37], off
	v_mov_b64_e32 v[38:39], v[208:209]
	v_mov_b64_e32 v[40:41], v[210:211]
	s_nop 0
	v_mov_b64_e32 v[42:43], v[212:213]
	v_mov_b64_e32 v[44:45], v[214:215]
	v_pk_mul_f32 v[46:47], v[60:61], v[72:73] op_sel_hi:[1,0]
	v_pk_mul_f32 v[48:49], v[62:63], v[72:73] op_sel_hi:[1,0]
	v_pk_mul_f32 v[50:51], v[64:65], v[72:73] op_sel_hi:[1,0]
	v_pk_mul_f32 v[52:53], v[66:67], v[72:73] op_sel_hi:[1,0]
	v_pk_mul_f32 v[56:57], v[58:59], v[72:73] op_sel_hi:[1,0]
	v_max_f32_e64 v33, |v36|, |v37|
	v_pk_mul_f32 v[54:55], v[68:69], v[72:73] op_sel_hi:[1,0]
	v_max3_f32 v33, |v34|, |v35|, v33
	v_pk_fma_f32 v[38:39], v[38:39], v[46:47], v[42:43]
	v_pk_fma_f32 v[40:41], v[40:41], v[48:49], v[44:45]
	v_cvt_pk_bf16_f32 v42, v38, v39
	v_cvt_pk_bf16_f32 v43, v40, v41
	global_store_dwordx4 v[24:25], v[38:41], off offset:1024
	v_mov_b64_e32 v[42:43], v[216:217]
	v_mov_b64_e32 v[44:45], v[218:219]
	s_nop 0
	v_mov_b64_e32 v[46:47], v[220:221]
	v_mov_b64_e32 v[48:49], v[222:223]
	v_max_f32_e64 v58, |v40|, |v41|
	v_max3_f32 v58, |v38|, |v39|, v58
	v_max3_f32 v33, v33, 0, v58
	v_pk_fma_f32 v[42:43], v[50:51], v[42:43], v[46:47]
	v_pk_fma_f32 v[44:45], v[52:53], v[44:45], v[48:49]
	v_cvt_pk_bf16_f32 v46, v42, v43
	v_cvt_pk_bf16_f32 v47, v44, v45
	global_store_dwordx4 v[24:25], v[42:45], off offset:2048
	v_mov_b64_e32 v[46:47], v[224:225]
	v_mov_b64_e32 v[48:49], v[226:227]
	s_nop 0
	v_mov_b64_e32 v[50:51], v[228:229]
	v_mov_b64_e32 v[52:53], v[230:231]
	v_max_f32_e64 v58, |v44|, |v45|
	v_max3_f32 v58, |v42|, |v43|, v58
	v_pk_fma_f32 v[48:49], v[56:57], v[48:49], v[52:53]
	v_pk_fma_f32 v[46:47], v[54:55], v[46:47], v[50:51]
	v_max_f32_e64 v50, |v48|, |v49|
	v_max3_f32 v50, |v46|, |v47|, v50
	v_max3_f32 v33, v33, v58, v50
	ds_bpermute_b32 v50, v26, v33
	global_store_dwordx4 v[24:25], v[46:49], off offset:3072
	v_cvt_pk_bf16_f32 v53, v48, v49
	s_waitcnt lgkmcnt(0)
	v_max_f32_e32 v50, v50, v50
	v_max_f32_e32 v33, v33, v50
	ds_bpermute_b32 v50, v27, v33
	s_waitcnt lgkmcnt(0)
	v_max_f32_e32 v50, v50, v50
	v_max_f32_e32 v33, v33, v50
	ds_bpermute_b32 v50, v28, v33
	s_waitcnt lgkmcnt(0)
	v_max_f32_e32 v50, v50, v50
	v_max_f32_e32 v33, v33, v50
	ds_bpermute_b32 v50, v29, v33
	s_waitcnt lgkmcnt(0)
	v_max_f32_e32 v50, v50, v50
	v_max_f32_e32 v33, v33, v50
	ds_bpermute_b32 v52, v30, v33
	v_lshlrev_b64 v[50:51], 10, v[0:1]
	v_lshl_add_u64 v[50:51], v[22:23], 0, v[50:51]
	s_waitcnt lgkmcnt(0)
	v_max_f32_e32 v52, v52, v52
	v_max_f32_e32 v33, v33, v52
	ds_bpermute_b32 v54, v31, v33
	v_cvt_pk_bf16_f32 v52, v46, v47
	s_waitcnt lgkmcnt(0)
	v_max_f32_e32 v24, v54, v54
	v_max_f32_e32 v24, v33, v24
	v_div_scale_f32 v25, s[2:3], v24, v24, s14
	v_rcp_f32_e32 v33, v25
	v_div_scale_f32 v52, vcc, s14, v24, s14
	v_cmp_lt_f32_e64 s[6:7], 0, v24
	v_fma_f32 v53, -v25, v33, 1.0
	v_fmac_f32_e32 v33, v53, v33
	v_mul_f32_e32 v53, v52, v33
	v_fma_f32 v54, -v25, v53, v52
	v_fmac_f32_e32 v53, v54, v33
	v_fma_f32 v25, -v25, v53, v52
	v_div_fmas_f32 v25, v25, v33, v53
	v_div_fixup_f32 v25, v25, v24, s14
	v_cndmask_b32_e64 v25, 0, v25, s[6:7]
	v_mul_f32_e32 v33, v34, v25
	v_mul_f32_e32 v34, v35, v25
	v_mul_f32_e32 v35, v36, v25
	v_mul_f32_e32 v36, v37, v25
	v_mul_f32_e32 v37, v38, v25
	v_mul_f32_e32 v38, v39, v25
	v_mul_f32_e32 v39, v40, v25
	v_mul_f32_e32 v40, v41, v25
	v_rndne_f32_e32 v33, v33
	v_rndne_f32_e32 v34, v34
	v_rndne_f32_e32 v35, v35
	v_rndne_f32_e32 v36, v36
	v_rndne_f32_e32 v37, v37
	v_rndne_f32_e32 v38, v38
	v_mul_f32_e32 v41, v42, v25
	v_mul_f32_e32 v42, v43, v25
	v_mul_f32_e32 v43, v44, v25
	v_mul_f32_e32 v44, v45, v25
	v_mul_f32_e32 v45, v46, v25
	v_mul_f32_e32 v46, v47, v25
	v_mul_f32_e32 v47, v48, v25
	v_mul_f32_e32 v25, v49, v25
	v_rndne_f32_e32 v39, v39
	v_rndne_f32_e32 v40, v40
	v_add_f32_e32 v48, v33, v34
	v_add_f32_e32 v49, v35, v36
	v_cvt_i32_f32_e32 v33, v33
	v_cvt_i32_f32_e32 v34, v34
	v_cvt_i32_f32_e32 v36, v36
	v_add_f32_e32 v52, v37, v38
	v_cvt_i32_f32_e32 v38, v38
	v_rndne_f32_e32 v41, v41
	v_rndne_f32_e32 v42, v42
	v_rndne_f32_e32 v43, v43
	v_rndne_f32_e32 v44, v44
	v_cvt_i32_f32_sdwa v35, v35 dst_sel:WORD_1 dst_unused:UNUSED_PAD src0_sel:DWORD
	v_add_f32_e32 v53, v39, v40
	v_add_f32_e32 v48, v48, v49
	v_rndne_f32_e32 v45, v45
	v_rndne_f32_e32 v46, v46
	v_rndne_f32_e32 v47, v47
	v_rndne_f32_e32 v25, v25
	v_add_f32_e32 v54, v41, v42
	v_add_f32_e32 v55, v43, v44
	v_add_f32_e32 v49, v52, v53
	v_add_f32_e32 v48, 0, v48
	v_add_f32_e32 v56, v45, v46
	v_add_f32_e32 v57, v47, v25
	v_add_f32_e32 v52, v54, v55
	v_add_f32_e32 v48, v49, v48
	v_add_f32_e32 v53, v56, v57
	v_lshlrev_b32_e32 v34, 8, v34
	v_perm_b32 v33, v36, v33, s15
	v_lshlrev_b32_e32 v36, 8, v38
	v_add_f32_e32 v38, v52, v48
	v_cvt_i32_f32_e32 v37, v37
	v_cvt_i32_f32_sdwa v39, v39 dst_sel:WORD_1 dst_unused:UNUSED_PAD src0_sel:DWORD
	v_cvt_i32_f32_e32 v40, v40
	v_and_b32_e32 v35, 0xff0000, v35
	v_and_b32_e32 v34, 0xff00, v34
	v_add_f32_e32 v38, v53, v38
	v_or3_b32 v33, v33, v34, v35
	ds_bpermute_b32 v34, v26, v38
	v_and_b32_e32 v36, 0xff00, v36
	global_store_dword v[50:51], v33, off
	v_and_b32_e32 v33, 0xff0000, v39
	v_perm_b32 v35, v40, v37, s15
	v_or3_b32 v33, v35, v36, v33
	global_store_dword v[50:51], v33, off offset:256
	s_waitcnt lgkmcnt(0)
	v_add_f32_e32 v33, v38, v34
	ds_bpermute_b32 v34, v27, v33
	v_cvt_i32_f32_e32 v36, v42
	v_cvt_i32_f32_e32 v35, v41
	v_cvt_i32_f32_sdwa v37, v43 dst_sel:WORD_1 dst_unused:UNUSED_PAD src0_sel:DWORD
	v_cvt_i32_f32_e32 v38, v44
	s_waitcnt lgkmcnt(0)
	v_add_f32_e32 v33, v33, v34
	ds_bpermute_b32 v34, v28, v33
	v_lshlrev_b32_e32 v36, 8, v36
	v_and_b32_e32 v36, 0xff00, v36
	v_and_b32_e32 v37, 0xff0000, v37
	v_perm_b32 v35, v38, v35, s15
	s_waitcnt lgkmcnt(0)
	v_add_f32_e32 v33, v33, v34
	ds_bpermute_b32 v34, v29, v33
	v_or3_b32 v35, v35, v36, v37
	v_cvt_i32_f32_e32 v36, v46
	v_cvt_i32_f32_e32 v38, v25
	global_store_dword v[50:51], v35, off offset:512
	s_waitcnt lgkmcnt(0)
	v_add_f32_e32 v33, v33, v34
	ds_bpermute_b32 v34, v30, v33
	v_lshlrev_b32_e32 v25, 8, v36
	v_cvt_i32_f32_e32 v35, v45
	v_cvt_i32_f32_sdwa v37, v47 dst_sel:WORD_1 dst_unused:UNUSED_PAD src0_sel:DWORD
	v_and_b32_e32 v36, 0xff00, v25
	s_waitcnt lgkmcnt(0)
	v_add_f32_e32 v25, v33, v34
	ds_bpermute_b32 v33, v31, v25
	v_and_b32_e32 v34, 0xff0000, v37
	v_perm_b32 v35, v38, v35, s15
	v_or3_b32 v34, v35, v36, v34
	global_store_dword v[50:51], v34, off offset:768
	s_and_saveexec_b64 s[2:3], s[4:5]
	s_cbranch_execz .LBB0_843
	v_div_scale_f32 v34, s[18:19], s14, s14, v24
	v_rcp_f32_e32 v35, v34
	s_waitcnt lgkmcnt(0)
	v_add_f32_e32 v33, v25, v33
	v_fma_f32 v25, -v34, v35, 1.0
	v_fmac_f32_e32 v35, v25, v35
	v_div_scale_f32 v25, vcc, v24, s14, v24
	v_mul_f32_e32 v36, v25, v35
	v_fma_f32 v37, -v34, v36, v25
	v_fmac_f32_e32 v36, v37, v35
	v_fma_f32 v25, -v34, v36, v25
	v_div_fmas_f32 v25, v25, v35, v36
	v_div_fixup_f32 v24, v25, s14, v24
	v_cndmask_b32_e64 v36, 0, v24, s[6:7]
	v_lshlrev_b64 v[24:25], 2, v[0:1]
	v_lshl_add_u64 v[34:35], s[68:69], 0, v[24:25]
	v_lshl_add_u64 v[24:25], s[70:71], 0, v[24:25]
	global_store_dword v[34:35], v36, off
	global_store_dword v[24:25], v33, off
	s_branch .LBB0_843
